# attention main loop: pipelined LDS fragment reads + softmax VALU interleaved under MFMAs (bit-identical math)
# baseline (speedup 1.0000x reference)
.LBB0_711:
	s_waitcnt lgkmcnt(10)
	v_mfma_f32_32x32x16_bf16 v[48:63], v[198:201], v[240:243], v[48:63]
	v_add_u32_e32 v177, s100, v153
	ds_read_b128 v[198:201], v177 offset:36864
	v_sub_f32_e32 v186, v64, v160
	v_exp_f32_e32 v186, v186
	v_sub_f32_e32 v187, v65, v160
	v_exp_f32_e32 v187, v187
	v_add_f32_e32 v234, v186, v234
	v_add_f32_e32 v234, v187, v234
	v_cvt_pk_bf16_f32 v248, v186, v187
	s_waitcnt lgkmcnt(10)
	v_mfma_f32_32x32x16_bf16 v[32:47], v[202:205], v[240:243], v[32:47]
	v_add_u32_e32 v177, s100, v152
	ds_read_b128 v[202:205], v177 offset:24576
	v_sub_f32_e32 v170, v66, v160
	v_exp_f32_e32 v170, v170
	v_sub_f32_e32 v171, v67, v160
	v_exp_f32_e32 v171, v171
	v_add_f32_e32 v234, v170, v234
	v_add_f32_e32 v234, v171, v234
	v_cvt_pk_bf16_f32 v249, v170, v171
	s_waitcnt lgkmcnt(10)
	v_mfma_f32_32x32x16_bf16 v[16:31], v[206:209], v[240:243], v[16:31]
	v_add_u32_e32 v177, s100, v152
	ds_read_b128 v[206:209], v177 offset:28672
	v_sub_f32_e32 v172, v68, v160
	v_exp_f32_e32 v172, v172
	v_sub_f32_e32 v173, v69, v160
	v_exp_f32_e32 v173, v173
	v_add_f32_e32 v234, v172, v234
	v_add_f32_e32 v234, v173, v234
	v_cvt_pk_bf16_f32 v250, v172, v173
	s_waitcnt lgkmcnt(10)
	v_mfma_f32_32x32x16_bf16 v[0:15], v[210:213], v[240:243], v[0:15]
	v_add_u32_e32 v177, s100, v152
	ds_read_b128 v[210:213], v177 offset:32768
	v_sub_f32_e32 v186, v70, v160
	v_exp_f32_e32 v186, v186
	v_sub_f32_e32 v187, v71, v160
	v_exp_f32_e32 v187, v187
	v_add_f32_e32 v234, v186, v234
	v_add_f32_e32 v234, v187, v234
	v_cvt_pk_bf16_f32 v251, v186, v187
	s_waitcnt lgkmcnt(10)
	v_mfma_f32_32x32x16_bf16 v[48:63], v[214:217], v[244:247], v[48:63]
	v_add_u32_e32 v177, s100, v152
	ds_read_b128 v[214:217], v177 offset:36864
	v_sub_f32_e32 v170, v72, v160
	v_exp_f32_e32 v170, v170
	v_sub_f32_e32 v171, v73, v160
	v_exp_f32_e32 v171, v171
	v_add_f32_e32 v234, v170, v234
	v_add_f32_e32 v234, v171, v234
	v_cvt_pk_bf16_f32 v252, v170, v171
	s_waitcnt lgkmcnt(10)
	v_mfma_f32_32x32x16_bf16 v[32:47], v[218:221], v[244:247], v[32:47]
	v_sub_f32_e32 v172, v74, v160
	v_exp_f32_e32 v172, v172
	v_sub_f32_e32 v173, v75, v160
	v_exp_f32_e32 v173, v173
	v_add_f32_e32 v234, v172, v234
	v_add_f32_e32 v234, v173, v234
	v_cvt_pk_bf16_f32 v253, v172, v173
	s_waitcnt lgkmcnt(9)
	v_mfma_f32_32x32x16_bf16 v[16:31], v[222:225], v[244:247], v[16:31]
	v_sub_f32_e32 v186, v76, v160
	v_exp_f32_e32 v186, v186
	v_sub_f32_e32 v187, v77, v160
	v_exp_f32_e32 v187, v187
	v_add_f32_e32 v234, v186, v234
	v_add_f32_e32 v234, v187, v234
	v_cvt_pk_bf16_f32 v254, v186, v187
	s_waitcnt lgkmcnt(8)
	v_mfma_f32_32x32x16_bf16 v[0:15], v[226:229], v[244:247], v[0:15]
	v_sub_f32_e32 v170, v78, v160
	v_exp_f32_e32 v170, v170
	v_sub_f32_e32 v171, v79, v160
	v_exp_f32_e32 v171, v171
	v_add_f32_e32 v234, v170, v234
	v_add_f32_e32 v234, v171, v234
	v_cvt_pk_bf16_f32 v255, v170, v171
	s_waitcnt lgkmcnt(7)
	v_mfma_f32_32x32x16_bf16 v[48:63], v[230:233], v[248:251], v[48:63]
	s_waitcnt lgkmcnt(6)
	v_mfma_f32_32x32x16_bf16 v[32:47], v[178:181], v[248:251], v[32:47]
	s_waitcnt lgkmcnt(5)
	v_mfma_f32_32x32x16_bf16 v[16:31], v[182:185], v[248:251], v[16:31]
	s_waitcnt lgkmcnt(4)
	v_mfma_f32_32x32x16_bf16 v[0:15], v[198:201], v[248:251], v[0:15]
	s_waitcnt lgkmcnt(3)
	v_mfma_f32_32x32x16_bf16 v[48:63], v[202:205], v[252:255], v[48:63]
	s_waitcnt lgkmcnt(2)
	v_mfma_f32_32x32x16_bf16 v[32:47], v[206:209], v[252:255], v[32:47]
	s_waitcnt lgkmcnt(1)
	v_mfma_f32_32x32x16_bf16 v[16:31], v[210:213], v[252:255], v[16:31]
	s_waitcnt lgkmcnt(0)
	v_mfma_f32_32x32x16_bf16 v[0:15], v[214:217], v[252:255], v[0:15]
	v_add_f32_e32 v147, v147, v234
	s_setprio 0
	s_waitcnt vmcnt(0)
	s_add_i32 s14, s14, 1
	s_add_i32 s13, s13, 64
	v_lshl_add_u64 v[148:149], v[148:149], 0, s[18:19]
	s_cmp_eq_u32 s17, s14
	v_lshl_add_u64 v[150:151], v[150:151], 0, s[18:19]
	s_waitcnt vmcnt(0)
	s_barrier
	s_cbranch_scc1 .LBB0_722
.LBB0_712:
	s_bitcmp1_b32 s14, 0
	s_cselect_b32 s100, 0, 0xa000
	v_add_u32_e32 v169, s100, v168
	v_add_u32_e32 v174, s100, v167
	v_add_u32_e32 v175, s100, v166
	v_add_u32_e32 v176, s100, v163
	ds_read_b128 v[178:181], v169
	ds_read_b128 v[182:185], v174
	ds_read_b128 v[198:201], v175
	ds_read_b128 v[202:205], v176
	ds_read_b128 v[206:209], v169 offset:128
	ds_read_b128 v[210:213], v174 offset:128
	ds_read_b128 v[214:217], v175 offset:128
	ds_read_b128 v[218:221], v176 offset:128
	ds_read_b128 v[222:225], v169 offset:256
	ds_read_b128 v[226:229], v174 offset:256
	ds_read_b128 v[230:233], v175 offset:256
	s_add_i32 s12, s12, 1
	s_lshl_b32 s11, s12, 6
	s_and_b64 vcc, exec, s[36:37]
	s_mov_b64 s[6:7], -1
	s_cbranch_vccnz .LBB0_718
	s_add_i32 s6, s13, 0xffff7000
	s_cmpk_gt_u32 s6, 0xfff
	s_mov_b64 s[6:7], -1
	s_cbranch_scc0 .LBB0_715
	s_add_i32 s10, s1, s13
	s_mov_b64 s[6:7], 0

.LBB0_720:
	s_ashr_i32 s11, s10, 31
	s_lshl_b64 s[6:7], s[10:11], 3
	s_add_u32 s6, s6, s4
	s_addc_u32 s7, s7, s5
	s_mulk_i32 s7, 0x180
	s_mul_hi_u32 s10, s6, 0x180
	s_add_i32 s10, s10, s7
	s_mulk_i32 s6, 0x180
	s_add_u32 s6, s15, s6
	s_addc_u32 s7, s16, s10
	s_bitcmp1_b32 s14, 0
	s_cselect_b32 s10, 0xa000, 0
	v_add_u32_e32 v66, s10, v162
	v_add_u32_e32 v67, 0x2000, v66
	v_readfirstlane_b32 s11, v66
	v_lshl_add_u64 v[64:65], s[6:7], 0, v[164:165]
	s_mov_b32 m0, s11
	v_readfirstlane_b32 s11, v67
	global_load_lds_dwordx4 v[64:65], off
	v_lshl_add_u64 v[64:65], s[6:7], 0, v[154:155]
	s_mov_b32 m0, s11
	v_add_u32_e32 v66, 0x4000, v66
	global_load_lds_dwordx4 v[64:65], off
	v_lshl_add_u64 v[64:65], s[6:7], 0, v[156:157]
	v_readfirstlane_b32 s6, v66
	s_mov_b32 m0, s6
	s_cselect_b32 s7, 0, 0xa000
	s_add_i32 s6, s10, 0
	global_load_lds_dwordx4 v[64:65], off
	v_add_u32_e32 v64, s6, v161
	v_add_u32_e32 v65, 0x6000, v64
	v_add_u32_e32 v64, 0x8000, v64
	v_readfirstlane_b32 s10, v65
	s_mov_b32 m0, s10
	v_readfirstlane_b32 s10, v64
	global_load_lds_dwordx4 v[150:151], off
	s_mov_b32 m0, s10
	s_add_i32 s7, s7, 0
	global_load_lds_dwordx4 v[148:149], off
	s_setprio 1
	s_waitcnt lgkmcnt(10)
	v_mfma_f32_32x32x16_bf16 v[80:95], v[178:181], v[116:119], 0
	ds_read_b128 v[178:181], v176 offset:256
	s_waitcnt lgkmcnt(10)
	v_mfma_f32_32x32x16_bf16 v[80:95], v[182:185], v[124:127], v[80:95]
	ds_read_b128 v[182:185], v169 offset:12288
	s_waitcnt lgkmcnt(10)
	v_mfma_f32_32x32x16_bf16 v[80:95], v[198:201], v[132:135], v[80:95]
	ds_read_b128 v[198:201], v174 offset:12288
	s_waitcnt lgkmcnt(10)
	v_mfma_f32_32x32x16_bf16 v[80:95], v[202:205], v[136:139], v[80:95]
	ds_read_b128 v[202:205], v175 offset:12288
	s_waitcnt lgkmcnt(10)
	v_mfma_f32_32x32x16_bf16 v[80:95], v[206:209], v[104:107], v[80:95]
	ds_read_b128 v[206:209], v176 offset:12288
	s_waitcnt lgkmcnt(10)
	v_mfma_f32_32x32x16_bf16 v[80:95], v[210:213], v[112:115], v[80:95]
	ds_read_b128 v[210:213], v169 offset:12416
	s_waitcnt lgkmcnt(10)
	v_mfma_f32_32x32x16_bf16 v[80:95], v[214:217], v[120:123], v[80:95]
	ds_read_b128 v[214:217], v174 offset:12416
	s_waitcnt lgkmcnt(10)
	v_mfma_f32_32x32x16_bf16 v[80:95], v[218:221], v[128:131], v[80:95]
	ds_read_b128 v[218:221], v175 offset:12416
	s_waitcnt lgkmcnt(10)
	v_mfma_f32_32x32x16_bf16 v[80:95], v[222:225], v[100:103], v[80:95]
	ds_read_b128 v[222:225], v176 offset:12416
	s_waitcnt lgkmcnt(10)
	v_mfma_f32_32x32x16_bf16 v[80:95], v[226:229], v[96:99], v[80:95]
	ds_read_b128 v[226:229], v169 offset:12544
	s_waitcnt lgkmcnt(10)
	v_mfma_f32_32x32x16_bf16 v[80:95], v[230:233], v[140:143], v[80:95]
	ds_read_b128 v[230:233], v174 offset:12544
	s_waitcnt lgkmcnt(10)
	v_mfma_f32_32x32x16_bf16 v[80:95], v[178:181], v[108:111], v[80:95]
	ds_read_b128 v[178:181], v175 offset:12544
	s_waitcnt lgkmcnt(10)
	v_mfma_f32_32x32x16_bf16 v[64:79], v[182:185], v[116:119], 0
	ds_read_b128 v[182:185], v176 offset:12544
	s_waitcnt lgkmcnt(10)
	v_mfma_f32_32x32x16_bf16 v[64:79], v[198:201], v[124:127], v[64:79]
	v_add_u32_e32 v177, s100, v159
	ds_read_b128 v[198:201], v177 offset:24576
	s_waitcnt lgkmcnt(10)
	v_mfma_f32_32x32x16_bf16 v[64:79], v[202:205], v[132:135], v[64:79]
	ds_read_b128 v[202:205], v177 offset:28672
	s_waitcnt lgkmcnt(10)
	v_mfma_f32_32x32x16_bf16 v[64:79], v[206:209], v[136:139], v[64:79]
	ds_read_b128 v[206:209], v177 offset:32768
	v_sub_f32_e32 v170, v80, v160
	v_exp_f32_e32 v170, v170
	v_sub_f32_e32 v171, v81, v160
	v_exp_f32_e32 v171, v171
	v_add_f32_e32 v234, 0, v170
	v_add_f32_e32 v234, v171, v234
	s_waitcnt lgkmcnt(10)
	v_mfma_f32_32x32x16_bf16 v[64:79], v[210:213], v[104:107], v[64:79]
	ds_read_b128 v[210:213], v177 offset:36864
	v_cvt_pk_bf16_f32 v240, v170, v171
	v_sub_f32_e32 v172, v82, v160
	v_exp_f32_e32 v172, v172
	v_sub_f32_e32 v173, v83, v160
	v_exp_f32_e32 v173, v173
	v_add_f32_e32 v234, v172, v234
	s_waitcnt lgkmcnt(10)
	v_mfma_f32_32x32x16_bf16 v[64:79], v[214:217], v[112:115], v[64:79]
	v_add_u32_e32 v177, s100, v158
	ds_read_b128 v[214:217], v177 offset:24576
	v_add_f32_e32 v234, v173, v234
	v_cvt_pk_bf16_f32 v241, v172, v173
	v_sub_f32_e32 v186, v84, v160
	v_exp_f32_e32 v186, v186
	v_sub_f32_e32 v187, v85, v160
	v_exp_f32_e32 v187, v187
	s_waitcnt lgkmcnt(10)
	v_mfma_f32_32x32x16_bf16 v[64:79], v[218:221], v[120:123], v[64:79]
	ds_read_b128 v[218:221], v177 offset:28672
	v_add_f32_e32 v234, v186, v234
	v_add_f32_e32 v234, v187, v234
	v_cvt_pk_bf16_f32 v242, v186, v187
	v_sub_f32_e32 v170, v86, v160
	v_exp_f32_e32 v170, v170
	v_sub_f32_e32 v171, v87, v160
	s_waitcnt lgkmcnt(10)
	v_mfma_f32_32x32x16_bf16 v[64:79], v[222:225], v[128:131], v[64:79]
	ds_read_b128 v[222:225], v177 offset:32768
	v_exp_f32_e32 v171, v171
	v_add_f32_e32 v234, v170, v234
	v_add_f32_e32 v234, v171, v234
	v_cvt_pk_bf16_f32 v243, v170, v171
	v_sub_f32_e32 v172, v88, v160
	v_exp_f32_e32 v172, v172
	s_waitcnt lgkmcnt(10)
	v_mfma_f32_32x32x16_bf16 v[64:79], v[226:229], v[100:103], v[64:79]
	ds_read_b128 v[226:229], v177 offset:36864
	v_sub_f32_e32 v173, v89, v160
	v_exp_f32_e32 v173, v173
	v_add_f32_e32 v234, v172, v234
	v_add_f32_e32 v234, v173, v234
	v_cvt_pk_bf16_f32 v244, v172, v173
	v_sub_f32_e32 v186, v90, v160
	s_waitcnt lgkmcnt(10)
	v_mfma_f32_32x32x16_bf16 v[64:79], v[230:233], v[96:99], v[64:79]
	v_add_u32_e32 v177, s100, v153
	ds_read_b128 v[230:233], v177 offset:24576
	v_exp_f32_e32 v186, v186
	v_sub_f32_e32 v187, v91, v160
	v_exp_f32_e32 v187, v187
	v_add_f32_e32 v234, v186, v234
	v_add_f32_e32 v234, v187, v234
	v_cvt_pk_bf16_f32 v245, v186, v187
	s_waitcnt lgkmcnt(10)
	v_mfma_f32_32x32x16_bf16 v[64:79], v[178:181], v[140:143], v[64:79]
	ds_read_b128 v[178:181], v177 offset:28672
	v_sub_f32_e32 v170, v92, v160
	v_exp_f32_e32 v170, v170
	v_sub_f32_e32 v171, v93, v160
	v_exp_f32_e32 v171, v171
	v_add_f32_e32 v234, v170, v234
	v_add_f32_e32 v234, v171, v234
	s_waitcnt lgkmcnt(10)
	v_mfma_f32_32x32x16_bf16 v[64:79], v[182:185], v[108:111], v[64:79]
	ds_read_b128 v[182:185], v177 offset:32768
	v_cvt_pk_bf16_f32 v246, v170, v171
	v_sub_f32_e32 v172, v94, v160
	v_exp_f32_e32 v172, v172
	v_sub_f32_e32 v173, v95, v160
	v_exp_f32_e32 v173, v173
	v_add_f32_e32 v234, v172, v234
	v_add_f32_e32 v234, v173, v234
	v_cvt_pk_bf16_f32 v247, v172, v173
	v_max_f32_e32 v235, v80, v81
	v_max3_f32 v235, v235, v82, v83
	v_max3_f32 v235, v235, v84, v85
	v_max3_f32 v235, v235, v86, v87
	v_max3_f32 v235, v235, v88, v89
	v_max3_f32 v235, v235, v90, v91
	v_max3_f32 v235, v235, v92, v93
	v_max3_f32 v235, v235, v94, v95
	v_max3_f32 v169, v235, v64, v65
	v_max3_f32 v169, v169, v66, v67
	v_max3_f32 v169, v169, v68, v69
	v_max3_f32 v169, v169, v70, v71
	v_max3_f32 v169, v169, v72, v73
	v_max3_f32 v169, v169, v74, v75
	v_max3_f32 v169, v169, v76, v77
	v_max3_f32 v169, v169, v78, v79
	v_mov_b32_e32 v170, v169
	s_nop 1
	v_permlane32_swap_b32_e32 v169, v170
	v_max_f32_e32 v170, v170, v170
	v_max_f32_e32 v169, v169, v169
	v_max_f32_e32 v169, v169, v170
	v_sub_f32_e32 v170, v169, v160
	v_cmp_ge_f32_e32 vcc, s29, v170
	s_cmp_eq_u64 vcc, exec
	s_cbranch_scc1 .LBB0_711
	v_max_f32_e32 v169, v169, v169
	v_max_f32_e32 v170, v160, v160
	v_max_f32_e32 v169, v170, v169
	v_sub_f32_e32 v160, v160, v169
	v_exp_f32_e32 v160, v160
	s_nop 0
	v_pk_mul_f32 v[62:63], v[62:63], v[160:161] op_sel_hi:[1,0]
	v_pk_mul_f32 v[60:61], v[60:61], v[160:161] op_sel_hi:[1,0]
	v_pk_mul_f32 v[58:59], v[58:59], v[160:161] op_sel_hi:[1,0]
	v_pk_mul_f32 v[56:57], v[56:57], v[160:161] op_sel_hi:[1,0]
	v_pk_mul_f32 v[54:55], v[54:55], v[160:161] op_sel_hi:[1,0]
	v_pk_mul_f32 v[52:53], v[52:53], v[160:161] op_sel_hi:[1,0]
	v_pk_mul_f32 v[50:51], v[50:51], v[160:161] op_sel_hi:[1,0]
	v_pk_mul_f32 v[48:49], v[48:49], v[160:161] op_sel_hi:[1,0]
	v_pk_mul_f32 v[46:47], v[46:47], v[160:161] op_sel_hi:[1,0]
	v_pk_mul_f32 v[44:45], v[44:45], v[160:161] op_sel_hi:[1,0]
	v_pk_mul_f32 v[42:43], v[42:43], v[160:161] op_sel_hi:[1,0]
	v_pk_mul_f32 v[40:41], v[40:41], v[160:161] op_sel_hi:[1,0]
	v_pk_mul_f32 v[38:39], v[38:39], v[160:161] op_sel_hi:[1,0]
	v_pk_mul_f32 v[36:37], v[36:37], v[160:161] op_sel_hi:[1,0]
	v_pk_mul_f32 v[34:35], v[34:35], v[160:161] op_sel_hi:[1,0]
	v_pk_mul_f32 v[32:33], v[32:33], v[160:161] op_sel_hi:[1,0]
	v_pk_mul_f32 v[30:31], v[30:31], v[160:161] op_sel_hi:[1,0]
	v_pk_mul_f32 v[28:29], v[28:29], v[160:161] op_sel_hi:[1,0]
	v_pk_mul_f32 v[26:27], v[26:27], v[160:161] op_sel_hi:[1,0]
	v_pk_mul_f32 v[24:25], v[24:25], v[160:161] op_sel_hi:[1,0]
	v_pk_mul_f32 v[22:23], v[22:23], v[160:161] op_sel_hi:[1,0]
	v_pk_mul_f32 v[20:21], v[20:21], v[160:161] op_sel_hi:[1,0]
	v_pk_mul_f32 v[18:19], v[18:19], v[160:161] op_sel_hi:[1,0]
	v_pk_mul_f32 v[16:17], v[16:17], v[160:161] op_sel_hi:[1,0]
	v_pk_mul_f32 v[14:15], v[14:15], v[160:161] op_sel_hi:[1,0]
	v_pk_mul_f32 v[12:13], v[12:13], v[160:161] op_sel_hi:[1,0]
	v_pk_mul_f32 v[10:11], v[10:11], v[160:161] op_sel_hi:[1,0]
	v_pk_mul_f32 v[8:9], v[8:9], v[160:161] op_sel_hi:[1,0]
	v_pk_mul_f32 v[6:7], v[6:7], v[160:161] op_sel_hi:[1,0]
	v_pk_mul_f32 v[4:5], v[4:5], v[160:161] op_sel_hi:[1,0]
	v_pk_mul_f32 v[2:3], v[2:3], v[160:161] op_sel_hi:[1,0]
	v_pk_mul_f32 v[0:1], v[0:1], v[160:161] op_sel_hi:[1,0]
	v_mul_f32_e32 v147, v147, v160
	v_mov_b32_e32 v160, v169
	v_sub_f32_e32 v170, v80, v160
	v_exp_f32_e32 v170, v170
	v_sub_f32_e32 v171, v81, v160
	v_exp_f32_e32 v171, v171
	v_add_f32_e32 v234, 0, v170
	v_add_f32_e32 v234, v171, v234
	v_cvt_pk_bf16_f32 v240, v170, v171
	v_sub_f32_e32 v172, v82, v160
	v_exp_f32_e32 v172, v172
	v_sub_f32_e32 v173, v83, v160
	v_exp_f32_e32 v173, v173
	v_add_f32_e32 v234, v172, v234
	v_add_f32_e32 v234, v173, v234
	v_cvt_pk_bf16_f32 v241, v172, v173
	v_sub_f32_e32 v186, v84, v160
	v_exp_f32_e32 v186, v186
	v_sub_f32_e32 v187, v85, v160
	v_exp_f32_e32 v187, v187
	v_add_f32_e32 v234, v186, v234
	v_add_f32_e32 v234, v187, v234
	v_cvt_pk_bf16_f32 v242, v186, v187
	v_sub_f32_e32 v170, v86, v160
	v_exp_f32_e32 v170, v170
	v_sub_f32_e32 v171, v87, v160
	v_exp_f32_e32 v171, v171
	v_add_f32_e32 v234, v170, v234
	v_add_f32_e32 v234, v171, v234
	v_cvt_pk_bf16_f32 v243, v170, v171
	v_sub_f32_e32 v172, v88, v160
	v_exp_f32_e32 v172, v172
	v_sub_f32_e32 v173, v89, v160
	v_exp_f32_e32 v173, v173
	v_add_f32_e32 v234, v172, v234
	v_add_f32_e32 v234, v173, v234
	v_cvt_pk_bf16_f32 v244, v172, v173
	v_sub_f32_e32 v186, v90, v160
	v_exp_f32_e32 v186, v186
	v_sub_f32_e32 v187, v91, v160
	v_exp_f32_e32 v187, v187
	v_add_f32_e32 v234, v186, v234
	v_add_f32_e32 v234, v187, v234
	v_cvt_pk_bf16_f32 v245, v186, v187
	v_sub_f32_e32 v170, v92, v160
	v_exp_f32_e32 v170, v170
	v_sub_f32_e32 v171, v93, v160
	v_exp_f32_e32 v171, v171
	v_add_f32_e32 v234, v170, v234
	v_add_f32_e32 v234, v171, v234
	v_cvt_pk_bf16_f32 v246, v170, v171
	v_sub_f32_e32 v172, v94, v160
	v_exp_f32_e32 v172, v172
	v_sub_f32_e32 v173, v95, v160
	v_exp_f32_e32 v173, v173
	v_add_f32_e32 v234, v172, v234
	v_add_f32_e32 v234, v173, v234
	v_cvt_pk_bf16_f32 v247, v172, v173
	v_max_f32_e32 v235, v80, v81
	v_max3_f32 v235, v235, v82, v83
	v_max3_f32 v235, v235, v84, v85
	v_max3_f32 v235, v235, v86, v87
	v_max3_f32 v235, v235, v88, v89
	v_max3_f32 v235, v235, v90, v91
	v_max3_f32 v235, v235, v92, v93
	v_max3_f32 v235, v235, v94, v95
	s_branch .LBB0_711

	.amdhsa_kernel fwd_megakernel
		.amdhsa_group_segment_fixed_size 0
		.amdhsa_private_segment_fixed_size 0
		.amdhsa_kernarg_size 560
		.amdhsa_user_sgpr_count 2
		.amdhsa_user_sgpr_dispatch_ptr 0
		.amdhsa_user_sgpr_queue_ptr 0
		.amdhsa_user_sgpr_kernarg_segment_ptr 1
		.amdhsa_user_sgpr_dispatch_id 0
		.amdhsa_user_sgpr_kernarg_preload_length 0
		.amdhsa_user_sgpr_kernarg_preload_offset 0
		.amdhsa_user_sgpr_private_segment_size 0
		.amdhsa_uses_dynamic_stack 0
		.amdhsa_enable_private_segment 0
		.amdhsa_system_sgpr_workgroup_id_x 1
		.amdhsa_system_sgpr_workgroup_id_y 0
		.amdhsa_system_sgpr_workgroup_id_z 0
		.amdhsa_system_sgpr_workgroup_info 0
		.amdhsa_system_vgpr_workitem_id 2
		.amdhsa_next_free_vgpr 256
		.amdhsa_next_free_sgpr 102
		.amdhsa_accum_offset 256
		.amdhsa_reserve_vcc 1
		.amdhsa_float_round_mode_32 0
		.amdhsa_float_round_mode_16_64 0
		.amdhsa_float_denorm_mode_32 3
		.amdhsa_float_denorm_mode_16_64 3
		.amdhsa_dx10_clamp 1
		.amdhsa_ieee_mode 1
		.amdhsa_fp16_overflow 0
		.amdhsa_tg_split 0
		.amdhsa_exception_fp_ieee_invalid_op 0
		.amdhsa_exception_fp_denorm_src 0
		.amdhsa_exception_fp_ieee_div_zero 0
		.amdhsa_exception_fp_ieee_overflow 0
		.amdhsa_exception_fp_ieee_underflow 0
		.amdhsa_exception_fp_ieee_inexact 0
		.amdhsa_exception_int_div_zero 0
	.end_amdhsa_kernel

amdhsa.kernels:
  - .agpr_count:     0
    .args:
      - .offset:         0
        .size:           304
        .value_kind:     by_value
      - .offset:         304
        .size:           4
        .value_kind:     hidden_block_count_x
      - .offset:         308
        .size:           4
        .value_kind:     hidden_block_count_y
      - .offset:         312
        .size:           4
        .value_kind:     hidden_block_count_z
      - .offset:         316
        .size:           2
        .value_kind:     hidden_group_size_x
      - .offset:         318
        .size:           2
        .value_kind:     hidden_group_size_y
      - .offset:         320
        .size:           2
        .value_kind:     hidden_group_size_z
      - .offset:         322
        .size:           2
        .value_kind:     hidden_remainder_x
      - .offset:         324
        .size:           2
        .value_kind:     hidden_remainder_y
      - .offset:         326
        .size:           2
        .value_kind:     hidden_remainder_z
      - .offset:         344
        .size:           8
        .value_kind:     hidden_global_offset_x
      - .offset:         352
        .size:           8
        .value_kind:     hidden_global_offset_y
      - .offset:         360
        .size:           8
        .value_kind:     hidden_global_offset_z
      - .offset:         368
        .size:           2
        .value_kind:     hidden_grid_dims
      - .offset:         392
        .size:           8
        .value_kind:     hidden_multigrid_sync_arg
      - .offset:         424
        .size:           4
        .value_kind:     hidden_dynamic_lds_size
    .group_segment_fixed_size: 0
    .kernarg_segment_align: 8
    .kernarg_segment_size: 560
    .language:       OpenCL C
    .language_version:
      - 2
      - 0
    .max_flat_workgroup_size: 512
    .name:           fwd_megakernel
    .private_segment_fixed_size: 0
    .sgpr_count:     108
    .sgpr_spill_count: 214
    .symbol:         fwd_megakernel.kd
    .uniform_work_group_size: 1
    .uses_dynamic_stack: false
    .vgpr_count:     256
    .vgpr_spill_count: 0
    .wavefront_size: 64
